# attention: next tile's V fragments also prefetched (end of PV), od_in ssq loads batched
# baseline (speedup 1.0000x reference)
.LBB0_736:
	v_mov_b32_e32 v14, v137
	v_mov_b32_e32 v15, v137
	s_addk_i32 s28, 0x100
	v_mul_u32_u24_e32 v147, 0xd0, v10
	v_mul_u32_u24_e32 v156, 0x90, v10
	v_lshlrev_b32_e32 v145, 2, v11
	v_mad_u64_u32 v[148:149], s[2:3], v140, 3, v[4:5]
	v_mad_u64_u32 v[150:151], s[2:3], v138, 3, v[2:3]
	v_mad_u64_u32 v[152:153], s[2:3], v136, 3, v[0:1]
	v_mov_b32_e32 v0, v137
	v_mov_b32_e32 v1, v137
	v_mov_b32_e32 v2, v137
	v_mov_b32_e32 v3, v137
	v_mov_b32_e32 v4, v137
	v_mov_b32_e32 v5, v137
	v_mov_b32_e32 v6, v137
	v_mov_b32_e32 v7, v137
	v_mov_b32_e32 v8, v137
	v_mov_b32_e32 v9, v137
	v_mov_b32_e32 v10, v137
	v_mov_b32_e32 v11, v137
	v_mov_b32_e32 v12, v137
	v_mov_b32_e32 v13, v137
	v_mov_b64_e32 v[30:31], v[14:15]
	s_lshr_b32 s46, s28, 6
	s_or_b32 s47, s44, 31
	s_mov_b32 s48, 0
	v_mov_b32_e32 v157, 0
	s_mov_b32 s49, 63
	v_mov_b64_e32 v[28:29], v[12:13]
	v_mov_b64_e32 v[26:27], v[10:11]
	v_mov_b64_e32 v[24:25], v[8:9]
	v_mov_b64_e32 v[22:23], v[6:7]
	v_mov_b64_e32 v[20:21], v[4:5]
	v_mov_b64_e32 v[18:19], v[2:3]
	v_mov_b64_e32 v[16:17], v[0:1]
	v_mov_b32_e32 v158, 0
	v_mov_b32_e32 v64, 0
	v_mov_b32_e32 v216, 0
	v_mov_b32_e32 v217, 0
	v_mov_b32_e32 v218, 0
	v_mov_b32_e32 v219, 0
	v_mov_b32_e32 v220, 0
	v_mov_b32_e32 v221, 0
	v_mov_b32_e32 v222, 0
	v_mov_b32_e32 v223, 0
	v_mov_b32_e32 v224, 0
	v_mov_b32_e32 v225, 0
	v_mov_b32_e32 v226, 0
	v_mov_b32_e32 v227, 0
	v_mov_b32_e32 v228, 0
	v_mov_b32_e32 v229, 0
	v_mov_b32_e32 v230, 0
	v_mov_b32_e32 v231, 0
	s_waitcnt vmcnt(0)
	v_add_u32_e32 v159, v147, v146
	ds_read_b128 v[168:171], v159
	ds_read_b128 v[192:195], v159 offset:6656
	ds_read_b128 v[172:175], v159 offset:32
	ds_read_b128 v[196:199], v159 offset:6688
	ds_read_b128 v[176:179], v159 offset:64
	ds_read_b128 v[200:203], v159 offset:6720
	ds_read_b128 v[180:183], v159 offset:96
	ds_read_b128 v[204:207], v159 offset:6752
	ds_read_b128 v[184:187], v159 offset:128
	ds_read_b128 v[208:211], v159 offset:6784
	ds_read_b128 v[188:191], v159 offset:160
	ds_read_b128 v[212:215], v159 offset:6816
	v_add_u32_e32 v232, v156, v146
	ds_read_b128 v[108:111], v232 offset:13312
	ds_read_b128 v[124:127], v232 offset:17920
	ds_read_b128 v[104:107], v232 offset:13344
	ds_read_b128 v[120:123], v232 offset:17952
	ds_read_b128 v[112:115], v232 offset:13376
	ds_read_b128 v[132:135], v232 offset:17984
	ds_read_b128 v[116:119], v232 offset:13408
	ds_read_b128 v[128:131], v232 offset:18016
	s_branch .LBB0_740

.LBB0_738:
	v_exp_f32_e32 v32, v32
	v_exp_f32_e32 v48, v48
	v_exp_f32_e32 v33, v33
	v_exp_f32_e32 v49, v49
	v_add_f32_e32 v65, 0, v32
	v_add_f32_e32 v66, 0, v48
	v_exp_f32_e32 v34, v34
	v_exp_f32_e32 v50, v50
	v_exp_f32_e32 v35, v35
	v_add_f32_e32 v65, v33, v65
	v_add_f32_e32 v66, v49, v66
	v_exp_f32_e32 v51, v51
	v_exp_f32_e32 v36, v36
	v_add_f32_e32 v65, v34, v65
	v_add_f32_e32 v66, v50, v66
	v_exp_f32_e32 v52, v52
	v_exp_f32_e32 v37, v37
	v_add_f32_e32 v65, v35, v65
	v_add_f32_e32 v66, v51, v66
	v_exp_f32_e32 v53, v53
	v_exp_f32_e32 v38, v38
	v_add_f32_e32 v65, v36, v65
	v_add_f32_e32 v66, v52, v66
	v_exp_f32_e32 v54, v54
	v_exp_f32_e32 v39, v39
	v_add_f32_e32 v65, v37, v65
	v_add_f32_e32 v66, v53, v66
	v_exp_f32_e32 v55, v55
	v_exp_f32_e32 v40, v40
	v_add_f32_e32 v65, v38, v65
	v_add_f32_e32 v66, v54, v66
	v_exp_f32_e32 v56, v56
	v_exp_f32_e32 v57, v57
	v_add_f32_e32 v65, v39, v65
	v_add_f32_e32 v66, v55, v66
	v_cvt_pk_bf16_f32 v67, v34, v35
	v_add_f32_e32 v65, v40, v65
	v_add_f32_e32 v66, v56, v66
	v_cvt_pk_bf16_f32 v68, v36, v37
	v_add_f32_e32 v70, v57, v66
	v_cvt_pk_bf16_f32 v66, v32, v33
	v_cvt_pk_bf16_f32 v69, v38, v39
	v_exp_f32_e32 v41, v41
	v_exp_f32_e32 v42, v42
	v_mfma_f32_32x32x16_bf16 v[0:15], v[108:111], v[66:69], v[0:15]
	v_exp_f32_e32 v43, v43
	v_exp_f32_e32 v44, v44
	v_exp_f32_e32 v45, v45
	v_exp_f32_e32 v46, v46
	v_exp_f32_e32 v47, v47
	v_exp_f32_e32 v58, v58
	v_add_f32_e32 v65, v41, v65
	v_mfma_f32_32x32x16_bf16 v[16:31], v[124:127], v[66:69], v[16:31]
	v_cvt_pk_bf16_f32 v66, v40, v41
	v_cvt_pk_bf16_f32 v67, v42, v43
	v_cvt_pk_bf16_f32 v68, v44, v45
	v_cvt_pk_bf16_f32 v69, v46, v47
	v_exp_f32_e32 v59, v59
	v_add_f32_e32 v65, v42, v65
	v_mfma_f32_32x32x16_bf16 v[0:15], v[104:107], v[66:69], v[0:15]
	v_add_f32_e32 v70, v58, v70
	v_exp_f32_e32 v60, v60
	v_exp_f32_e32 v61, v61
	v_exp_f32_e32 v62, v62
	v_exp_f32_e32 v63, v63
	v_mfma_f32_32x32x16_bf16 v[16:31], v[120:123], v[66:69], v[16:31]
	v_cvt_pk_bf16_f32 v66, v48, v49
	v_cvt_pk_bf16_f32 v67, v50, v51
	v_cvt_pk_bf16_f32 v68, v52, v53
	v_cvt_pk_bf16_f32 v69, v54, v55
	v_add_f32_e32 v65, v43, v65
	v_add_f32_e32 v70, v59, v70
	v_mfma_f32_32x32x16_bf16 v[0:15], v[112:115], v[66:69], v[0:15]
	v_add_f32_e32 v65, v44, v65
	v_add_f32_e32 v70, v60, v70
	v_add_f32_e32 v65, v45, v65
	v_mfma_f32_32x32x16_bf16 v[16:31], v[132:135], v[66:69], v[16:31]
	v_cvt_pk_bf16_f32 v66, v56, v57
	v_cvt_pk_bf16_f32 v67, v58, v59
	v_cvt_pk_bf16_f32 v68, v60, v61
	v_cvt_pk_bf16_f32 v69, v62, v63
	v_add_f32_e32 v70, v61, v70
	v_add_f32_e32 v65, v46, v65
	v_mfma_f32_32x32x16_bf16 v[0:15], v[116:119], v[66:69], v[0:15]
	v_add_f32_e32 v70, v62, v70
	v_add_f32_e32 v65, v47, v65
	v_add_f32_e32 v70, v63, v70
	v_mfma_f32_32x32x16_bf16 v[16:31], v[128:131], v[66:69], v[16:31]
	v_add_f32_e32 v65, v65, v70
	v_add_f32_e32 v158, v158, v65
	s_add_i32 s26, s48, 1
	s_cmp_ge_u32 s26, s46
	s_cbranch_scc1 .Lvpf_done
	s_add_i32 s27, s49, 1
	s_cmp_gt_i32 s27, s47
	s_cbranch_scc1 .Lvpf_done
	s_and_b32 s26, s26, 3
	s_mulk_i32 s26, 0x5800
	v_add3_u32 v232, s26, v156, v146
	ds_read_b128 v[108:111], v232 offset:13312
	ds_read_b128 v[124:127], v232 offset:17920
	ds_read_b128 v[104:107], v232 offset:13344
	ds_read_b128 v[120:123], v232 offset:17952
	ds_read_b128 v[112:115], v232 offset:13376
	ds_read_b128 v[132:135], v232 offset:17984
	ds_read_b128 v[116:119], v232 offset:13408
	ds_read_b128 v[128:131], v232 offset:18016
.Lvpf_done:
.LBB0_739:
	s_add_i32 s48, s48, 1
	s_add_i32 s49, s49, 64
	v_lshl_add_u64 v[148:149], v[148:149], 0, v[140:141]
	v_lshl_add_u64 v[150:151], v[150:151], 0, v[138:139]
	s_cmp_ge_u32 s48, s46
	v_lshl_add_u64 v[152:153], v[152:153], 0, v[136:137]
	s_cbranch_scc1 .LBB0_759

.LBB0_743:
	s_sub_i32 s26, s49, 63
	s_cmp_le_i32 s26, s47
	s_cselect_b64 s[28:29], -1, 0
	s_cmp_gt_i32 s26, s47
	s_cbranch_scc1 .LBB0_756
	s_and_b32 s26, s48, 3
	s_mulk_i32 s26, 0x5800
	s_add_i32 s26, s26, 0
	s_waitcnt lgkmcnt(8)
	v_mfma_f32_32x32x16_bf16 v[32:47], v[168:171], v[96:99], v[216:231]
	v_mfma_f32_32x32x16_bf16 v[48:63], v[192:195], v[96:99], v[216:231]
	v_mfma_f32_32x32x16_bf16 v[32:47], v[172:175], v[80:83], v[32:47]
	v_mfma_f32_32x32x16_bf16 v[48:63], v[196:199], v[80:83], v[48:63]
	v_mfma_f32_32x32x16_bf16 v[32:47], v[176:179], v[84:87], v[32:47]
	v_mfma_f32_32x32x16_bf16 v[48:63], v[200:203], v[84:87], v[48:63]
	v_mfma_f32_32x32x16_bf16 v[32:47], v[180:183], v[88:91], v[32:47]
	v_mfma_f32_32x32x16_bf16 v[48:63], v[204:207], v[88:91], v[48:63]
	v_mfma_f32_32x32x16_bf16 v[32:47], v[184:187], v[92:95], v[32:47]
	v_mfma_f32_32x32x16_bf16 v[48:63], v[208:211], v[92:95], v[48:63]
	v_mfma_f32_32x32x16_bf16 v[32:47], v[188:191], v[100:103], v[32:47]
	v_mfma_f32_32x32x16_bf16 v[48:63], v[212:215], v[100:103], v[48:63]
	s_mov_b64 s[26:27], -1
	s_and_b64 vcc, exec, s[2:3]
	s_cbranch_vccnz .LBB0_757
